# attn: output-rescale block moved into the rare max-update path; per-tile alpha test removed (3 fewer instr per tile)
# speedup vs baseline: 1.0104x; 1.0020x over previous
; #define LAS __attribute__((address_space(3)))
; __device__ __forceinline__ void qkt(f32x16& p0, f32x16& p1, const LAS unsigned char* Ks, const bf16x8* qr, const f32x16& negm, int r32, int hi) {
;   bf16x8 kf[12];
; #pragma unroll
;   for (int d0 = 0; d0 < 6; ++d0) { const int cb = (d0 * 16 + hi * 8) * 2;
;     kf[2 * d0] = *(const LAS bf16x8*)(Ks + KSWZ(r32, cb)); kf[2 * d0 + 1] = *(const LAS bf16x8*)(Ks + KSWZ(32 + r32, cb)); }
;   SBAR();
;   p0 = __builtin_amdgcn_mfma_f32_32x32x16_bf16(kf[0], qr[0], negm, 0, 0, 0); p1 = __builtin_amdgcn_mfma_f32_32x32x16_bf16(kf[1], qr[0], negm, 0, 0, 0);
; #pragma unroll
;   for (int d0 = 1; d0 < 6; ++d0) { p0 = __builtin_amdgcn_mfma_f32_32x32x16_bf16(kf[2 * d0], qr[d0], p0, 0, 0, 0); p1 = __builtin_amdgcn_mfma_f32_32x32x16_bf16(kf[2 * d0 + 1], qr[d0], p1, 0, 0, 0); }
; }
; __device__ __forceinline__ int v_st(int k, int c) { const int kk = (k & ~0xC) | ((k & 4) << 1) | ((k & 8) >> 1); return ((kk >> 3) * 4 + (c >> 5)) * 512 + ((kk & 7) * 32 + (c & 31)) * 2; }
; __device__ __forceinline__ int v_rd_base(int lane) { return ((lane & 3) << 3) | (((lane >> 2) & 3) << 6) | (((lane >> 4) & 1) << 5) | (((lane >> 5) & 1) << 8); }
; template <int OFF> __device__ __forceinline__ s16x4 tr_read(int vb) {
;   s16x4 r; asm volatile("ds_read_b64_tr_b16 %0, %1 offset:%2" : "=&v"(r) : "v"(vb), "i"(OFF) : "memory"); return r;
; }
; __device__ __forceinline__ void pv_d0(f32x16* o, int vb, bf16x8 pa0, bf16x8 pa1, bf16x8 pa2, bf16x8 pa3) {
;   const s16x4 a0 = tr_read<v_rd_off(0, 0, 0)>(vb), b0 = tr_read<v_rd_off(0, 0, 1)>(vb), a1 = tr_read<v_rd_off(0, 1, 0)>(vb), b1 = tr_read<v_rd_off(0, 1, 1)>(vb);
;   const s16x4 a2 = tr_read<v_rd_off(0, 2, 0)>(vb), b2 = tr_read<v_rd_off(0, 2, 1)>(vb), a3 = tr_read<v_rd_off(0, 3, 0)>(vb), b3 = tr_read<v_rd_off(0, 3, 1)>(vb);
;   const s16x4 c0 = tr_read<v_rd_off(1, 0, 0)>(vb), d0 = tr_read<v_rd_off(1, 0, 1)>(vb), c1 = tr_read<v_rd_off(1, 1, 0)>(vb), d1 = tr_read<v_rd_off(1, 1, 1)>(vb);
;   const s16x4 c2 = tr_read<v_rd_off(1, 2, 0)>(vb), d2 = tr_read<v_rd_off(1, 2, 1)>(vb), c3 = tr_read<v_rd_off(1, 3, 0)>(vb), d3 = tr_read<v_rd_off(1, 3, 1)>(vb);
;   asm volatile("s_waitcnt lgkmcnt(0)" ::: "memory"); SBAR();
;     ...
;   o[0] = __builtin_amdgcn_mfma_f32_32x32x16_bf16(pa0, PK(a0, b0), o[0], 0, 0, 0); o[1] = __builtin_amdgcn_mfma_f32_32x32x16_bf16(pa0, PK(c0, d0), o[1], 0, 0, 0);
.Lmy_attn_m1:
	ds_read_b64_tr_b16 v[70:71], v174 offset:0x1000
	ds_read_b64_tr_b16 v[72:73], v174 offset:0x1800
	ds_read_b64_tr_b16 v[162:163], v174 offset:0x1200
	ds_read_b64_tr_b16 v[164:165], v174 offset:0x1a00
	ds_read_b64_tr_b16 v[74:75], v174 offset:0x2000
	ds_read_b64_tr_b16 v[76:77], v174 offset:0x2800
	ds_read_b64_tr_b16 v[166:167], v174 offset:0x2200
	ds_read_b64_tr_b16 v[168:169], v174 offset:0x2a00
	ds_read_b64_tr_b16 v[78:79], v174 offset:0x3000
	ds_read_b64_tr_b16 v[80:81], v174 offset:0x3800
	ds_read_b64_tr_b16 v[170:171], v174 offset:0x3200
	ds_read_b64_tr_b16 v[172:173], v174 offset:0x3a00
	s_waitcnt lgkmcnt(14)
	v_mfma_f32_32x32x16_bf16 v[34:49], v[62:65], v[66:69], v[34:49]
	s_waitcnt lgkmcnt(12)
	v_mfma_f32_32x32x16_bf16 v[18:33], v[62:65], v[158:161], v[18:33]
	s_waitcnt lgkmcnt(10)
	v_mfma_f32_32x32x16_bf16 v[34:49], v[50:53], v[70:73], v[34:49]
	s_waitcnt lgkmcnt(8)
	v_mfma_f32_32x32x16_bf16 v[18:33], v[50:53], v[162:165], v[18:33]
	s_waitcnt lgkmcnt(6)
	v_mfma_f32_32x32x16_bf16 v[34:49], v[54:57], v[74:77], v[34:49]
	s_waitcnt lgkmcnt(4)
	v_mfma_f32_32x32x16_bf16 v[18:33], v[54:57], v[166:169], v[18:33]
	v_add_u32_e32 v54, s5, v146
	v_add_u32_e32 v55, v54, v147
	ds_read_b128 v[50:53], v55 offset:49152
	ds_read_b128 v[158:161], v55 offset:57344
	v_add_u32_e32 v55, v54, v148
	ds_read_b128 v[162:165], v55 offset:49152
	ds_read_b128 v[166:169], v55 offset:57344
	v_add_u32_e32 v55, v54, v149
	s_waitcnt lgkmcnt(6)
	v_mfma_f32_32x32x16_bf16 v[34:49], v[58:61], v[78:81], v[34:49]
	s_waitcnt lgkmcnt(4)
	v_mfma_f32_32x32x16_bf16 v[18:33], v[58:61], v[170:173], v[18:33]
	ds_read_b128 v[170:173], v55 offset:49152
	ds_read_b128 v[178:181], v55 offset:57344
	v_add_u32_e32 v55, v54, v150
	ds_read_b128 v[182:185], v55 offset:49152
	ds_read_b128 v[186:189], v55 offset:57344
	v_add_u32_e32 v55, v54, v151
	v_add_u32_e32 v54, v54, v152
	ds_read_b128 v[190:193], v55 offset:49152
	ds_read_b128 v[194:197], v55 offset:57344
	ds_read_b128 v[198:201], v54 offset:49152
	ds_read_b128 v[202:205], v54 offset:57344
	s_waitcnt lgkmcnt(11)
	v_mfma_f32_32x32x16_bf16 v[66:81], v[50:53], v[82:85], v[2:17]
	s_waitcnt lgkmcnt(9)
	v_mfma_f32_32x32x16_bf16 v[66:81], v[162:165], v[86:89], v[66:81]
	s_waitcnt lgkmcnt(7)
	v_mfma_f32_32x32x16_bf16 v[66:81], v[170:173], v[90:93], v[66:81]
	s_waitcnt lgkmcnt(5)
	v_mfma_f32_32x32x16_bf16 v[66:81], v[182:185], v[94:97], v[66:81]
	s_waitcnt lgkmcnt(3)
	v_mfma_f32_32x32x16_bf16 v[66:81], v[190:193], v[98:101], v[66:81]
	s_waitcnt lgkmcnt(1)
	v_mfma_f32_32x32x16_bf16 v[66:81], v[198:201], v[102:105], v[66:81]
	s_waitcnt lgkmcnt(0)
	v_mfma_f32_32x32x16_bf16 v[50:65], v[158:161], v[82:85], v[2:17]
	v_mfma_f32_32x32x16_bf16 v[50:65], v[166:169], v[86:89], v[50:65]
	v_mfma_f32_32x32x16_bf16 v[50:65], v[178:181], v[90:93], v[50:65]
	v_mfma_f32_32x32x16_bf16 v[50:65], v[186:189], v[94:97], v[50:65]
	v_mfma_f32_32x32x16_bf16 v[50:65], v[194:197], v[98:101], v[50:65]
	v_mfma_f32_32x32x16_bf16 v[50:65], v[202:205], v[102:105], v[50:65]
	s_setprio 0
	v_max3_f32 v158, v66, v67, v68
	v_max3_f32 v159, v69, v70, v71
	v_max3_f32 v158, v158, v72, v73
	v_max3_f32 v159, v159, v74, v75
	v_max3_f32 v158, v158, v76, v77
	v_max3_f32 v159, v159, v78, v79
	v_max3_f32 v158, v158, v80, v81
	s_nop 3
	v_max3_f32 v159, v159, v50, v51
	v_max3_f32 v158, v158, v52, v53
	v_max3_f32 v159, v159, v54, v55
	v_max3_f32 v158, v158, v56, v57
	v_max3_f32 v159, v159, v58, v59
	v_max3_f32 v158, v158, v60, v61
	v_max3_f32 v159, v159, v62, v63
	v_max3_f32 v158, v158, v64, v65
	v_max_f32_e32 v159, v158, v159
	v_cmp_ge_f32_e32 vcc, s93, v159
	s_cmp_eq_u64 vcc, exec
	s_barrier
	s_cbranch_scc0 .LBB0_540
.LBB0_525:
	v_exp_f32_e32 v66, v66
	v_exp_f32_e32 v222, v50
	v_exp_f32_e32 v67, v67
	v_exp_f32_e32 v223, v51
	v_exp_f32_e32 v68, v68
	v_exp_f32_e32 v224, v52
	v_exp_f32_e32 v69, v69
	v_exp_f32_e32 v225, v53
	v_exp_f32_e32 v70, v70
	v_exp_f32_e32 v226, v54
	v_exp_f32_e32 v71, v71
	v_exp_f32_e32 v227, v55
	v_exp_f32_e32 v72, v72
	v_exp_f32_e32 v228, v56
	v_exp_f32_e32 v73, v73
	v_exp_f32_e32 v229, v57
	v_exp_f32_e32 v74, v74
	v_exp_f32_e32 v230, v58
	v_exp_f32_e32 v75, v75
	v_exp_f32_e32 v231, v59
	v_exp_f32_e32 v76, v76
	v_exp_f32_e32 v232, v60
	v_exp_f32_e32 v77, v77
	v_exp_f32_e32 v233, v61
	v_exp_f32_e32 v78, v78
	v_exp_f32_e32 v234, v62
	v_exp_f32_e32 v79, v79
	v_exp_f32_e32 v235, v63
	v_exp_f32_e32 v80, v80
	v_exp_f32_e32 v236, v64
	v_exp_f32_e32 v81, v81
	v_exp_f32_e32 v237, v65
	v_cvt_pk_bf16_f32 v54, v66, v67
	v_cvt_pk_bf16_f32 v55, v68, v69
	v_cvt_pk_bf16_f32 v56, v70, v71
	v_cvt_pk_bf16_f32 v57, v72, v73
	v_cvt_pk_bf16_f32 v50, v74, v75
	v_cvt_pk_bf16_f32 v51, v76, v77
	v_cvt_pk_bf16_f32 v52, v78, v79
	v_cvt_pk_bf16_f32 v53, v80, v81
	v_cvt_pk_bf16_f32 v58, v222, v223
	v_cvt_pk_bf16_f32 v59, v224, v225
	v_cvt_pk_bf16_f32 v60, v226, v227
	v_cvt_pk_bf16_f32 v61, v228, v229
	v_cvt_pk_bf16_f32 v62, v230, v231
	v_cvt_pk_bf16_f32 v63, v232, v233
	v_cvt_pk_bf16_f32 v64, v234, v235
	v_cvt_pk_bf16_f32 v65, v236, v237
.LBB0_529:
	s_add_i32 s23, s65, s11
	s_add_i32 s0, s23, 1
	s_cmpk_gt_u32 s0, 0x83
	s_cbranch_scc1 .LBB0_531
	s_and_b64 s[24:25], s[54:55], exec
	s_cselect_b32 s1, s22, s10
	s_min_u32 s0, s0, 0x81
	v_add_u32_e32 v158, s1, v131
	s_lshl_b32 s0, s0, 6
	s_waitcnt vmcnt(3)
	ds_write_b128 v158, v[106:109]
	v_add_u32_e32 v106, s1, v133
	s_add_i32 s0, s4, s0
	ds_write_b128 v106, v[110:113]
	v_add_u32_e32 v106, s1, v145
	s_ashr_i32 s1, s0, 31
	ds_write_b128 v106, v[114:117] offset:49152
	s_lshl_b64 s[100:101], s[0:1], 11
	v_lshl_add_u64 v[106:107], v[216:217], 0, s[100:101]
	v_lshl_add_u64 v[110:111], v[218:219], 0, s[100:101]
	s_lshl_b64 s[100:101], s[0:1], 6
	v_lshl_add_u64 v[114:115], v[220:221], 0, s[100:101]
	global_load_dwordx4 v[106:109], v[106:107], off
	global_load_dwordx4 v[110:113], v[110:111], off
	global_load_dwordx4 v[114:117], v[114:115], off
; #define LAS __attribute__((address_space(3)))
; __device__ __forceinline__ void qkt(f32x16& p0, f32x16& p1, const LAS unsigned char* Ks, const bf16x8* qr, const f32x16& negm, int r32, int hi) {
;   bf16x8 kf[12];
; #pragma unroll
;   for (int d0 = 0; d0 < 6; ++d0) { const int cb = (d0 * 16 + hi * 8) * 2;
;     kf[2 * d0] = *(const LAS bf16x8*)(Ks + KSWZ(r32, cb)); kf[2 * d0 + 1] = *(const LAS bf16x8*)(Ks + KSWZ(32 + r32, cb)); }
;   SBAR();
;   p0 = __builtin_amdgcn_mfma_f32_32x32x16_bf16(kf[0], qr[0], negm, 0, 0, 0); p1 = __builtin_amdgcn_mfma_f32_32x32x16_bf16(kf[1], qr[0], negm, 0, 0, 0);
; #pragma unroll
;   for (int d0 = 1; d0 < 6; ++d0) { p0 = __builtin_amdgcn_mfma_f32_32x32x16_bf16(kf[2 * d0], qr[d0], p0, 0, 0, 0); p1 = __builtin_amdgcn_mfma_f32_32x32x16_bf16(kf[2 * d0 + 1], qr[d0], p1, 0, 0, 0); }
; }
; __device__ __forceinline__ int v_st(int k, int c) { const int kk = (k & ~0xC) | ((k & 4) << 1) | ((k & 8) >> 1); return ((kk >> 3) * 4 + (c >> 5)) * 512 + ((kk & 7) * 32 + (c & 31)) * 2; }
; __device__ __forceinline__ int v_rd_base(int lane) { return ((lane & 3) << 3) | (((lane >> 2) & 3) << 6) | (((lane >> 4) & 1) << 5) | (((lane >> 5) & 1) << 8); }
; template <int OFF> __device__ __forceinline__ s16x4 tr_read(int vb) {
;   s16x4 r; asm volatile("ds_read_b64_tr_b16 %0, %1 offset:%2" : "=&v"(r) : "v"(vb), "i"(OFF) : "memory"); return r;
; }
; __device__ __forceinline__ void pv_d0(f32x16* o, int vb, bf16x8 pa0, bf16x8 pa1, bf16x8 pa2, bf16x8 pa3) {
;   const s16x4 a0 = tr_read<v_rd_off(0, 0, 0)>(vb), b0 = tr_read<v_rd_off(0, 0, 1)>(vb), a1 = tr_read<v_rd_off(0, 1, 0)>(vb), b1 = tr_read<v_rd_off(0, 1, 1)>(vb);
;   const s16x4 a2 = tr_read<v_rd_off(0, 2, 0)>(vb), b2 = tr_read<v_rd_off(0, 2, 1)>(vb), a3 = tr_read<v_rd_off(0, 3, 0)>(vb), b3 = tr_read<v_rd_off(0, 3, 1)>(vb);
;   const s16x4 c0 = tr_read<v_rd_off(1, 0, 0)>(vb), d0 = tr_read<v_rd_off(1, 0, 1)>(vb), c1 = tr_read<v_rd_off(1, 1, 0)>(vb), d1 = tr_read<v_rd_off(1, 1, 1)>(vb);
;   const s16x4 c2 = tr_read<v_rd_off(1, 2, 0)>(vb), d2 = tr_read<v_rd_off(1, 2, 1)>(vb), c3 = tr_read<v_rd_off(1, 3, 0)>(vb), d3 = tr_read<v_rd_off(1, 3, 1)>(vb);
;   asm volatile("s_waitcnt lgkmcnt(0)" ::: "memory"); SBAR();
;     ...
;   o[0] = __builtin_amdgcn_mfma_f32_32x32x16_bf16(pa0, PK(a0, b0), o[0], 0, 0, 0); o[1] = __builtin_amdgcn_mfma_f32_32x32x16_bf16(pa0, PK(c0, d0), o[1], 0, 0, 0);
.LBB0_531:
	v_pk_add_f32 v[222:223], v[66:67], v[222:223]
	v_pk_add_f32 v[224:225], v[68:69], v[224:225]
	v_pk_add_f32 v[226:227], v[70:71], v[226:227]
	v_pk_add_f32 v[228:229], v[72:73], v[228:229]
	v_pk_add_f32 v[230:231], v[74:75], v[230:231]
	v_pk_add_f32 v[232:233], v[76:77], v[232:233]
	v_pk_add_f32 v[234:235], v[78:79], v[234:235]
	v_pk_add_f32 v[236:237], v[80:81], v[236:237]
	v_pk_add_f32 v[222:223], v[222:223], v[224:225]
	v_pk_add_f32 v[226:227], v[226:227], v[228:229]
	v_pk_add_f32 v[230:231], v[230:231], v[232:233]
	v_pk_add_f32 v[234:235], v[234:235], v[236:237]
	v_pk_add_f32 v[222:223], v[222:223], v[226:227]
	v_pk_add_f32 v[230:231], v[230:231], v[234:235]
	v_pk_add_f32 v[222:223], v[222:223], v[230:231]
	v_add_f32_e32 v222, v222, v223
	v_add_f32_e32 v157, v157, v222
	v_add_u32_e32 v174, s5, v156
	ds_read_b64_tr_b16 v[66:67], v174 offset:0
	ds_read_b64_tr_b16 v[68:69], v174 offset:0x800
	ds_read_b64_tr_b16 v[158:159], v174 offset:0x200
	ds_read_b64_tr_b16 v[160:161], v174 offset:0xa00
	s_waitcnt lgkmcnt(4)
	s_barrier
	s_setprio 2
	ds_read_b64_tr_b16 v[70:71], v174 offset:0x1000
	ds_read_b64_tr_b16 v[72:73], v174 offset:0x1800
	ds_read_b64_tr_b16 v[162:163], v174 offset:0x1200
	ds_read_b64_tr_b16 v[164:165], v174 offset:0x1a00
	ds_read_b64_tr_b16 v[74:75], v174 offset:0x2000
	ds_read_b64_tr_b16 v[76:77], v174 offset:0x2800
	ds_read_b64_tr_b16 v[166:167], v174 offset:0x2200
	ds_read_b64_tr_b16 v[168:169], v174 offset:0x2a00
	ds_read_b64_tr_b16 v[78:79], v174 offset:0x3000
	ds_read_b64_tr_b16 v[80:81], v174 offset:0x3800
	ds_read_b64_tr_b16 v[170:171], v174 offset:0x3200
	ds_read_b64_tr_b16 v[172:173], v174 offset:0x3a00
	s_waitcnt lgkmcnt(14)
	v_mfma_f32_32x32x16_bf16 v[34:49], v[54:57], v[66:69], v[34:49]
	s_waitcnt lgkmcnt(12)
	v_mfma_f32_32x32x16_bf16 v[18:33], v[54:57], v[158:161], v[18:33]
	v_add_u32_e32 v54, s10, v146
	v_add_u32_e32 v55, v54, v147
	s_waitcnt lgkmcnt(10)
	v_mfma_f32_32x32x16_bf16 v[34:49], v[50:53], v[70:73], v[34:49]
	s_waitcnt lgkmcnt(8)
	v_mfma_f32_32x32x16_bf16 v[18:33], v[50:53], v[162:165], v[18:33]
	ds_read_b128 v[50:53], v55 offset:49152
	ds_read_b128 v[158:161], v55 offset:57344
	v_add_u32_e32 v55, v54, v148
	s_waitcnt lgkmcnt(8)
	v_mfma_f32_32x32x16_bf16 v[34:49], v[58:61], v[74:77], v[34:49]
	s_waitcnt lgkmcnt(6)
	v_mfma_f32_32x32x16_bf16 v[18:33], v[58:61], v[166:169], v[18:33]
	ds_read_b128 v[162:165], v55 offset:49152
	ds_read_b128 v[166:169], v55 offset:57344
	v_add_u32_e32 v55, v54, v149
	s_waitcnt lgkmcnt(6)
	v_mfma_f32_32x32x16_bf16 v[34:49], v[62:65], v[78:81], v[34:49]
	s_waitcnt lgkmcnt(4)
	v_mfma_f32_32x32x16_bf16 v[18:33], v[62:65], v[170:173], v[18:33]
	ds_read_b128 v[170:173], v55 offset:49152
	ds_read_b128 v[178:181], v55 offset:57344
	v_add_u32_e32 v55, v54, v150
	ds_read_b128 v[182:185], v55 offset:49152
	ds_read_b128 v[186:189], v55 offset:57344
	v_add_u32_e32 v55, v54, v151
	v_add_u32_e32 v54, v54, v152
	ds_read_b128 v[190:193], v55 offset:49152
	ds_read_b128 v[194:197], v55 offset:57344
	ds_read_b128 v[198:201], v54 offset:49152
	ds_read_b128 v[202:205], v54 offset:57344
	s_waitcnt lgkmcnt(11)
	v_mfma_f32_32x32x16_bf16 v[66:81], v[50:53], v[82:85], v[2:17]
	s_waitcnt lgkmcnt(9)
	v_mfma_f32_32x32x16_bf16 v[66:81], v[162:165], v[86:89], v[66:81]
	s_waitcnt lgkmcnt(7)
	v_mfma_f32_32x32x16_bf16 v[66:81], v[170:173], v[90:93], v[66:81]
	s_waitcnt lgkmcnt(5)
	v_mfma_f32_32x32x16_bf16 v[66:81], v[182:185], v[94:97], v[66:81]
	s_waitcnt lgkmcnt(3)
	v_mfma_f32_32x32x16_bf16 v[66:81], v[190:193], v[98:101], v[66:81]
	s_waitcnt lgkmcnt(1)
	v_mfma_f32_32x32x16_bf16 v[66:81], v[198:201], v[102:105], v[66:81]
	s_waitcnt lgkmcnt(0)
	v_mfma_f32_32x32x16_bf16 v[50:65], v[158:161], v[82:85], v[2:17]
	v_mfma_f32_32x32x16_bf16 v[50:65], v[166:169], v[86:89], v[50:65]
	v_mfma_f32_32x32x16_bf16 v[50:65], v[178:181], v[90:93], v[50:65]
	v_mfma_f32_32x32x16_bf16 v[50:65], v[186:189], v[94:97], v[50:65]
	v_mfma_f32_32x32x16_bf16 v[50:65], v[194:197], v[98:101], v[50:65]
	v_mfma_f32_32x32x16_bf16 v[50:65], v[202:205], v[102:105], v[50:65]
	s_setprio 0
	v_max3_f32 v158, v66, v67, v68
	v_max3_f32 v159, v69, v70, v71
	v_max3_f32 v158, v158, v72, v73
	v_max3_f32 v159, v159, v74, v75
	v_max3_f32 v158, v158, v76, v77
	v_max3_f32 v159, v159, v78, v79
	v_max3_f32 v158, v158, v80, v81
	s_nop 3
	v_max3_f32 v159, v159, v50, v51
	v_max3_f32 v158, v158, v52, v53
	v_max3_f32 v159, v159, v54, v55
	v_max3_f32 v158, v158, v56, v57
	v_max3_f32 v159, v159, v58, v59
	v_max3_f32 v158, v158, v60, v61
	v_max3_f32 v159, v159, v62, v63
	v_max3_f32 v158, v158, v64, v65
	v_max_f32_e32 v159, v158, v159
	v_cmp_ge_f32_e32 vcc, s93, v159
	s_cmp_eq_u64 vcc, exec
	s_barrier
	s_cbranch_scc0 .LBB0_541
.LBB0_532:
	v_exp_f32_e32 v66, v66
	v_exp_f32_e32 v222, v50
	v_exp_f32_e32 v67, v67
	v_exp_f32_e32 v223, v51
	v_exp_f32_e32 v68, v68
	v_exp_f32_e32 v224, v52
	v_exp_f32_e32 v69, v69
	v_exp_f32_e32 v225, v53
	v_exp_f32_e32 v70, v70
	v_exp_f32_e32 v226, v54
	v_exp_f32_e32 v71, v71
	v_exp_f32_e32 v227, v55
	v_exp_f32_e32 v72, v72
	v_exp_f32_e32 v228, v56
	v_exp_f32_e32 v73, v73
	v_exp_f32_e32 v229, v57
	v_exp_f32_e32 v74, v74
	v_exp_f32_e32 v230, v58
	v_exp_f32_e32 v75, v75
	v_exp_f32_e32 v231, v59
	v_exp_f32_e32 v76, v76
	v_exp_f32_e32 v232, v60
	v_exp_f32_e32 v77, v77
	v_exp_f32_e32 v233, v61
	v_exp_f32_e32 v78, v78
	v_exp_f32_e32 v234, v62
	v_exp_f32_e32 v79, v79
	v_exp_f32_e32 v235, v63
	v_exp_f32_e32 v80, v80
	v_exp_f32_e32 v236, v64
	v_exp_f32_e32 v81, v81
	v_exp_f32_e32 v237, v65
	v_cvt_pk_bf16_f32 v62, v66, v67
	v_cvt_pk_bf16_f32 v63, v68, v69
	v_cvt_pk_bf16_f32 v64, v70, v71
	v_cvt_pk_bf16_f32 v65, v72, v73
	v_cvt_pk_bf16_f32 v50, v74, v75
	v_cvt_pk_bf16_f32 v51, v76, v77
	v_cvt_pk_bf16_f32 v52, v78, v79
	v_cvt_pk_bf16_f32 v53, v80, v81
	v_cvt_pk_bf16_f32 v54, v222, v223
	v_cvt_pk_bf16_f32 v55, v224, v225
	v_cvt_pk_bf16_f32 v56, v226, v227
	v_cvt_pk_bf16_f32 v57, v228, v229
	v_cvt_pk_bf16_f32 v58, v230, v231
	v_cvt_pk_bf16_f32 v59, v232, v233
	v_cvt_pk_bf16_f32 v60, v234, v235
	v_cvt_pk_bf16_f32 v61, v236, v237
.LBB0_536:
	s_cmpk_gt_u32 s11, 0x81
	s_cselect_b64 s[0:1], -1, 0
	s_and_b64 vcc, exec, s[0:1]
	s_cbranch_vccnz .LBB0_538
	s_add_i32 s23, s23, 2
	s_and_b64 s[24:25], s[54:55], exec
	s_cselect_b32 s24, s5, s22
	v_add_u32_e32 v158, s24, v131
	s_min_u32 s23, s23, 0x81
	s_waitcnt vmcnt(3)
	ds_write_b128 v158, v[118:121]
	v_add_u32_e32 v118, s24, v133
	s_lshl_b32 s23, s23, 6
	ds_write_b128 v118, v[122:125]
	v_add_u32_e32 v118, s24, v145
	s_add_i32 s24, s4, s23
	s_ashr_i32 s25, s24, 31
	ds_write_b128 v118, v[126:129] offset:49152
	s_lshl_b64 s[100:101], s[24:25], 11
	v_lshl_add_u64 v[118:119], v[216:217], 0, s[100:101]
	v_lshl_add_u64 v[122:123], v[218:219], 0, s[100:101]
	s_lshl_b64 s[100:101], s[24:25], 6
	v_lshl_add_u64 v[126:127], v[220:221], 0, s[100:101]
	global_load_dwordx4 v[118:121], v[118:119], off
	global_load_dwordx4 v[122:125], v[122:123], off
	global_load_dwordx4 v[126:129], v[126:127], off

; __device__ __forceinline__ void softmaxT(f32x16& p0, f32x16& p1, float& mref, f32x16& negm, float& l_reg, float& alpha, bf16x8& pa0, bf16x8& pa1, bf16x8& pa2, bf16x8& pa3) {
;     ...
;   { auto rr = __builtin_amdgcn_permlane32_swap(__float_as_uint(pmax), __float_as_uint(pmax), false, false);
;     pmax = __builtin_fmaxf(__uint_as_float(rr[0]), __uint_as_float(rr[1])); }
;   if (__builtin_expect(__all(pmax <= THR2), 1)) { alpha = 1.f; }
;   else { const float dl = __builtin_fmaxf(pmax, 0.f); mref += dl; alpha = __builtin_amdgcn_exp2f(-dl); l_reg *= alpha;
; #pragma unroll
;     for (int r = 0; r < 16; ++r) { p0[r] -= dl; p1[r] -= dl; negm[r] = -mref; }
;     asm volatile("" : "+v"(negm)); }
.LBB0_540:
	v_mov_b32_e32 v158, v159
	s_nop 1
	v_permlane32_swap_b32_e32 v158, v159
	v_max_f32_e32 v159, v158, v159
	v_max_f32_e32 v2, v159, v159
	v_max_f32_e32 v4, 0, v2
	v_exp_f32_e64 v158, -v4
	v_add_f32_e32 v153, v153, v4
	v_xor_b32_e32 v2, 0x80000000, v153
	v_pk_add_f32 v[66:67], v[66:67], v[4:5] op_sel_hi:[1,0] neg_lo:[0,1] neg_hi:[0,1]
	v_mul_f32_e32 v157, v157, v158
	v_pk_add_f32 v[50:51], v[50:51], v[4:5] op_sel_hi:[1,0] neg_lo:[0,1] neg_hi:[0,1]
	v_pk_add_f32 v[68:69], v[68:69], v[4:5] op_sel_hi:[1,0] neg_lo:[0,1] neg_hi:[0,1]
	v_pk_add_f32 v[52:53], v[52:53], v[4:5] op_sel_hi:[1,0] neg_lo:[0,1] neg_hi:[0,1]
	v_pk_add_f32 v[70:71], v[70:71], v[4:5] op_sel_hi:[1,0] neg_lo:[0,1] neg_hi:[0,1]
	v_pk_add_f32 v[54:55], v[54:55], v[4:5] op_sel_hi:[1,0] neg_lo:[0,1] neg_hi:[0,1]
	v_pk_add_f32 v[72:73], v[72:73], v[4:5] op_sel_hi:[1,0] neg_lo:[0,1] neg_hi:[0,1]
	v_pk_add_f32 v[56:57], v[56:57], v[4:5] op_sel_hi:[1,0] neg_lo:[0,1] neg_hi:[0,1]
	v_pk_add_f32 v[74:75], v[74:75], v[4:5] op_sel_hi:[1,0] neg_lo:[0,1] neg_hi:[0,1]
	v_pk_add_f32 v[58:59], v[58:59], v[4:5] op_sel_hi:[1,0] neg_lo:[0,1] neg_hi:[0,1]
	v_pk_add_f32 v[76:77], v[76:77], v[4:5] op_sel_hi:[1,0] neg_lo:[0,1] neg_hi:[0,1]
	v_pk_add_f32 v[60:61], v[60:61], v[4:5] op_sel_hi:[1,0] neg_lo:[0,1] neg_hi:[0,1]
	v_pk_add_f32 v[78:79], v[78:79], v[4:5] op_sel_hi:[1,0] neg_lo:[0,1] neg_hi:[0,1]
	v_pk_add_f32 v[62:63], v[62:63], v[4:5] op_sel_hi:[1,0] neg_lo:[0,1] neg_hi:[0,1]
	v_pk_add_f32 v[80:81], v[80:81], v[4:5] op_sel_hi:[1,0] neg_lo:[0,1] neg_hi:[0,1]
	v_pk_add_f32 v[64:65], v[64:65], v[4:5] op_sel_hi:[1,0] neg_lo:[0,1] neg_hi:[0,1]
	v_mov_b32_e32 v3, v2
	v_mov_b32_e32 v4, v2
	v_mov_b32_e32 v5, v2
	v_mov_b32_e32 v6, v2
	v_mov_b32_e32 v7, v2
	v_mov_b32_e32 v8, v2
	v_mov_b32_e32 v9, v2
	v_mov_b32_e32 v10, v2
	v_mov_b32_e32 v11, v2
	v_mov_b32_e32 v12, v2
	v_mov_b32_e32 v13, v2
	v_mov_b32_e32 v14, v2
	v_mov_b32_e32 v15, v2
	v_mov_b32_e32 v16, v2
	v_mov_b32_e32 v17, v2
	s_and_saveexec_b64 s[0:1], s[2:3]
	ds_write_b32 v155, v158
	s_or_b64 exec, exec, s[0:1]
	s_waitcnt lgkmcnt(0)
	v_add_u32_e32 v158, v154, v132
	ds_read_b128 v[162:165], v158 offset:96
	ds_read_b128 v[166:169], v158 offset:64
	ds_read_b128 v[170:173], v158 offset:32
	ds_read_b128 v[192:195], v158
	s_waitcnt lgkmcnt(3)
	v_pk_mul_f32 v[46:47], v[46:47], v[162:163]
	s_waitcnt lgkmcnt(2)
	v_pk_mul_f32 v[42:43], v[42:43], v[166:167]
	s_waitcnt lgkmcnt(1)
	v_pk_mul_f32 v[38:39], v[38:39], v[170:171]
	v_pk_mul_f32 v[48:49], v[48:49], v[164:165]
	v_pk_mul_f32 v[44:45], v[44:45], v[168:169]
	v_pk_mul_f32 v[40:41], v[40:41], v[172:173]
	s_waitcnt lgkmcnt(0)
	v_pk_mul_f32 v[36:37], v[36:37], v[194:195]
	v_pk_mul_f32 v[34:35], v[34:35], v[192:193]
	v_pk_mul_f32 v[30:31], v[30:31], v[162:163]
	v_pk_mul_f32 v[26:27], v[26:27], v[166:167]
	v_pk_mul_f32 v[22:23], v[22:23], v[170:171]
	v_pk_mul_f32 v[32:33], v[32:33], v[164:165]
	v_pk_mul_f32 v[28:29], v[28:29], v[168:169]
	v_pk_mul_f32 v[24:25], v[24:25], v[172:173]
	v_pk_mul_f32 v[20:21], v[20:21], v[194:195]
	v_pk_mul_f32 v[18:19], v[18:19], v[192:193]
	s_branch .LBB0_525
